# attention out-proj bias pre-add batched 8 rows in flight and split between the two kv-head workgroups
# speedup vs baseline: 1.0148x; 1.0041x over previous
; #define LAS __attribute__((address_space(3)))
; __device__ __forceinline__ void attn_phase(LAS unsigned char* lds, const bf16_t* QKV, bf16_t* O, bf16_t* XL, const float* bo, const float* qg, const float* kg, const float* sinks, const float* rel_bias, int vcu, int G, const int tid) {
;     ...
; #pragma unroll
;         for (int i = 0; i < 4; ++i) {
;             const int c = tid + 512 * i, key = c >> 3;
;             const long row = row_blk - 128 + key;
;             const bool ok = (nb > 0) || (key >= 128);
;             u32x4 kraw = (u32x4){0u, 0u, 0u, 0u}, vraw = (u32x4){0u, 0u, 0u, 0u};
;             if (ok) { const bf16_t* p = QKV + (size_t)row * NQKV + 1024 + hk * 64 + dc * 8; kraw = *(const u32x4*)p; vraw = *(const u32x4*)(p + 128); }
;             float kf[8];
;             kf[0] = bf_lo(kraw.x); kf[1] = bf_hi(kraw.x); kf[2] = bf_lo(kraw.y); kf[3] = bf_hi(kraw.y); kf[4] = bf_lo(kraw.z); kf[5] = bf_hi(kraw.z); kf[6] = bf_lo(kraw.w); kf[7] = bf_hi(kraw.w);
;             float ss = 0.f;
; #pragma unroll
;             for (int e = 0; e < 8; ++e) ss += kf[e] * kf[e];
;             ss += __shfl_xor(ss, 1); ss += __shfl_xor(ss, 2); ss += __shfl_xor(ss, 4);
;             const float rstd = 1.0f / sqrtf(ss * (1.f / 64.f) + EPS);
; #pragma unroll
;             for (int e = 0; e < 8; ++e) kf[e] = kf[e] * rstd * kgv[e];
;             u32x4 kw; kw.x = cvtpk(kf[0], kf[1]); kw.y = cvtpk(kf[2], kf[3]); kw.z = cvtpk(kf[4], kf[5]); kw.w = cvtpk(kf[6], kf[7]);
;             *(LAS u32x4*)(Ks + key * KS_STRIDE + dc * 16) = kw;
;             LAS unsigned char* vp = Vt + (dc * 8) * VT_STRIDE + key * 2;
;             *(LAS unsigned short*)(vp + 0 * VT_STRIDE) = (unsigned short)(vraw.x & 0xffffu); *(LAS unsigned short*)(vp + 1 * VT_STRIDE) = (unsigned short)(vraw.x >> 16);
;             *(LAS unsigned short*)(vp + 2 * VT_STRIDE) = (unsigned short)(vraw.y & 0xffffu); *(LAS unsigned short*)(vp + 3 * VT_STRIDE) = (unsigned short)(vraw.y >> 16);
;             *(LAS unsigned short*)(vp + 4 * VT_STRIDE) = (unsigned short)(vraw.z & 0xffffu); *(LAS unsigned short*)(vp + 5 * VT_STRIDE) = (unsigned short)(vraw.z >> 16);
;             *(LAS unsigned short*)(vp + 6 * VT_STRIDE) = (unsigned short)(vraw.w & 0xffffu); *(LAS unsigned short*)(vp + 7 * VT_STRIDE) = (unsigned short)(vraw.w >> 16);
;         }
;         if (hk == 0) {
; #pragma unroll 4
.LBB0_50:
	s_or_b64 exec, exec, s[16:17]
	s_waitcnt vmcnt(1)
	v_lshlrev_b32_e32 v18, 16, v0
	v_and_b32_e32 v19, 0xffff0000, v0
	v_lshlrev_b32_e32 v14, 16, v1
	v_and_b32_e32 v15, 0xffff0000, v1
	v_pk_mul_f32 v[0:1], v[18:19], v[18:19]
	v_pk_mul_f32 v[16:17], v[14:15], v[14:15]
	v_add_f32_e32 v0, v0, v1
	v_lshlrev_b32_e32 v12, 16, v2
	v_and_b32_e32 v13, 0xffff0000, v2
	v_add_f32_e32 v0, v16, v0
	v_lshlrev_b32_e32 v8, 16, v3
	v_and_b32_e32 v9, 0xffff0000, v3
	v_pk_mul_f32 v[2:3], v[12:13], v[12:13]
	v_add_f32_e32 v0, v17, v0
	v_add_f32_e32 v0, v2, v0
	v_pk_mul_f32 v[10:11], v[8:9], v[8:9]
	v_add_f32_e32 v0, v3, v0
	v_add_f32_e32 v0, v10, v0
	v_add_f32_e32 v0, v11, v0
	ds_bpermute_b32 v1, v105, v0
	s_cmp_eq_u32 s21, 0
	s_waitcnt lgkmcnt(0)
	v_add_f32_e32 v0, v0, v1
	ds_bpermute_b32 v1, v132, v0
	s_waitcnt lgkmcnt(0)
	v_add_f32_e32 v0, v0, v1
	ds_bpermute_b32 v1, v133, v0
	s_waitcnt lgkmcnt(0)
	v_add_f32_e32 v0, v0, v1
	v_fmamk_f32 v0, v0, 0x3c800000, v220
	v_mul_f32_e32 v1, 0x4f800000, v0
	v_cmp_gt_f32_e32 vcc, s30, v0
	s_nop 1
	v_cndmask_b32_e32 v0, v0, v1, vcc
	v_sqrt_f32_e32 v1, v0
	s_nop 0
	v_add_u32_e32 v2, -1, v1
	v_add_u32_e32 v3, 1, v1
	v_fma_f32 v10, -v2, v1, v0
	v_fma_f32 v11, -v3, v1, v0
	v_cmp_ge_f32_e64 s[16:17], 0, v10
	s_nop 1
	v_cndmask_b32_e64 v1, v1, v2, s[16:17]
	v_cmp_lt_f32_e64 s[16:17], 0, v11
	s_nop 1
	v_cndmask_b32_e64 v1, v1, v3, s[16:17]
	v_mul_f32_e32 v2, 0x37800000, v1
	v_cndmask_b32_e32 v1, v1, v2, vcc
	v_cmp_class_f32_e32 vcc, v0, v221
	s_nop 1
	v_cndmask_b32_e32 v0, v1, v0, vcc
	v_div_scale_f32 v1, s[16:17], v0, v0, 1.0
	v_rcp_f32_e32 v2, v1
	s_nop 0
	v_fma_f32 v3, -v1, v2, 1.0
	v_fmac_f32_e32 v2, v3, v2
	v_div_scale_f32 v3, vcc, 1.0, v0, 1.0
	v_mul_f32_e32 v10, v3, v2
	v_fma_f32 v11, -v1, v10, v3
	v_fmac_f32_e32 v10, v11, v2
	v_fma_f32 v1, -v1, v10, v3
	v_div_fmas_f32 v1, v1, v2, v10
	v_div_fixup_f32 v0, v1, v0, 1.0
	v_pk_mul_f32 v[2:3], v[0:1], v[18:19] op_sel_hi:[0,1]
	v_pk_mul_f32 v[10:11], v[0:1], v[14:15] op_sel_hi:[0,1]
	v_pk_mul_f32 v[12:13], v[0:1], v[12:13] op_sel_hi:[0,1]
	v_pk_mul_f32 v[0:1], v[0:1], v[8:9] op_sel_hi:[0,1]
	v_pk_mul_f32 v[2:3], v[84:85], v[2:3]
	v_pk_mul_f32 v[10:11], v[86:87], v[10:11]
	v_pk_mul_f32 v[12:13], v[80:81], v[12:13]
	v_pk_mul_f32 v[8:9], v[82:83], v[0:1]
	v_cvt_pk_bf16_f32 v0, v2, v3
	v_cvt_pk_bf16_f32 v1, v10, v11
	v_cvt_pk_bf16_f32 v2, v12, v13
	v_cvt_pk_bf16_f32 v3, v8, v9
	ds_write_b128 v174, v[0:3]
	s_waitcnt vmcnt(0)
	ds_write_b16 v175, v4 offset:36864
	ds_write_b16_d16_hi v175, v4 offset:37392
	ds_write_b16 v175, v5 offset:37920
	ds_write_b16_d16_hi v175, v5 offset:38448
	ds_write_b16 v175, v6 offset:38976
	ds_write_b16_d16_hi v175, v6 offset:39504
	ds_write_b16 v175, v7 offset:40032
	ds_write_b16_d16_hi v175, v7 offset:40560
	s_nop 0
	v_ashrrev_i32_e32 v1, 7, v192
	v_add_u32_e32 v1, s22, v1
	v_ashrrev_i32_e32 v2, 4, v1
	v_ashrrev_i32_e32 v3, 31, v2
	v_lshlrev_b64 v[2:3], 15, v[2:3]
	v_lshlrev_b32_e32 v1, 6, v1
	v_lshl_add_u64 v[2:3], v[108:109], 0, v[2:3]
	v_and_b32_e32 v176, 0x3c0, v1
	v_lshl_add_u64 v[2:3], v[2:3], 0, v[176:177]
	v_mov_b32_e32 v127, v177
	v_lshl_add_u64 v[16:17], v[2:3], 0, v[126:127]
	s_lshl_b32 vcc_lo, s21, 17
	s_mov_b32 vcc_hi, 0
	s_nop 0
	v_lshl_add_u64 v[16:17], v[16:17], 0, vcc
	global_load_dwordx4 v[228:231], v[110:111], off offset:16
	global_load_dwordx4 v[196:199], v[110:111], off
	s_mov_b32 s16, 0
; __device__ __forceinline__ unsigned cvtpk(float lo, float hi) { f32x2_t v = {lo, hi}; bf16x2_t b = __builtin_convertvector(v, bf16x2_t); return __builtin_bit_cast(unsigned, b); }
; __device__ __forceinline__ size_t xt_off(int row, int col) { return ((size_t)(row >> 4) * 32 + (col >> 5)) * 512 + (row & 15) * 32 + (col & 31); }
; __device__ __forceinline__ float bf_lo(unsigned u) { return __uint_as_float(u << 16); }
; __device__ __forceinline__ float bf_hi(unsigned u) { return __uint_as_float(u & 0xffff0000u); }
; __device__ __forceinline__ void attn_phase(LAS unsigned char* lds, const bf16_t* QKV, bf16_t* O, bf16_t* XL, const float* bo, const float* qg, const float* kg, const float* sinks, const float* rel_bias, int vcu, int G, const int tid) {
;     ...
;         if (hk == 0) {
; #pragma unroll 4
;             for (int i = 0; i < 32; ++i) { const int idx = tid + 512 * i, r = idx >> 7, c8 = idx & 127;
;                 u32x4* lp = (u32x4*)(XL + xt_off((int)row_blk + r, 8 * c8)); const u32x4 lv = *lp; const f32x4 b0 = *((const f32x4*)bo + 2 * c8), b1 = *((const f32x4*)bo + 2 * c8 + 1); u32x4 ln;
;                 ln.x = cvtpk(bf_lo(lv.x) + b0.x, bf_hi(lv.x) + b0.y); ln.y = cvtpk(bf_lo(lv.y) + b0.z, bf_hi(lv.y) + b0.w);
;                 ln.z = cvtpk(bf_lo(lv.z) + b1.x, bf_hi(lv.z) + b1.y); ln.w = cvtpk(bf_lo(lv.w) + b1.z, bf_hi(lv.w) + b1.w);
;                 *lp = ln; }
;         }
.Lab_loop:
	s_mov_b64 vcc, 0x8000
	v_lshl_add_u64 v[202:203], v[16:17], 0, vcc
	global_load_dwordx4 v[0:3], v[16:17], off
	global_load_dwordx4 v[4:7], v[16:17], off offset:256
	global_load_dwordx4 v[8:11], v[16:17], off offset:512
	global_load_dwordx4 v[12:15], v[16:17], off offset:768
	global_load_dwordx4 v[204:207], v[202:203], off
	global_load_dwordx4 v[208:211], v[202:203], off offset:256
	global_load_dwordx4 v[212:215], v[202:203], off offset:512
	global_load_dwordx4 v[216:219], v[202:203], off offset:768
	s_waitcnt vmcnt(0)
	v_lshlrev_b32_e32 v194, 16, v0
	v_and_b32_e32 v195, 0xffff0000, v0
	v_pk_add_f32 v[194:195], v[196:197], v[194:195]
	s_nop 0
	v_cvt_pk_bf16_f32 v0, v194, v195
	v_lshlrev_b32_e32 v226, 16, v1
	v_and_b32_e32 v227, 0xffff0000, v1
	v_pk_add_f32 v[226:227], v[198:199], v[226:227]
	s_nop 0
	v_cvt_pk_bf16_f32 v1, v226, v227
	v_lshlrev_b32_e32 v194, 16, v2
	v_and_b32_e32 v195, 0xffff0000, v2
	v_pk_add_f32 v[194:195], v[228:229], v[194:195]
	s_nop 0
	v_cvt_pk_bf16_f32 v2, v194, v195
	v_lshlrev_b32_e32 v226, 16, v3
	v_and_b32_e32 v227, 0xffff0000, v3
	v_pk_add_f32 v[226:227], v[230:231], v[226:227]
	s_nop 0
	v_cvt_pk_bf16_f32 v3, v226, v227
	global_store_dwordx4 v[16:17], v[0:3], off
	v_lshlrev_b32_e32 v194, 16, v4
	v_and_b32_e32 v195, 0xffff0000, v4
	v_pk_add_f32 v[194:195], v[196:197], v[194:195]
	s_nop 0
	v_cvt_pk_bf16_f32 v4, v194, v195
	v_lshlrev_b32_e32 v226, 16, v5
	v_and_b32_e32 v227, 0xffff0000, v5
	v_pk_add_f32 v[226:227], v[198:199], v[226:227]
	s_nop 0
	v_cvt_pk_bf16_f32 v5, v226, v227
	v_lshlrev_b32_e32 v194, 16, v6
	v_and_b32_e32 v195, 0xffff0000, v6
	v_pk_add_f32 v[194:195], v[228:229], v[194:195]
	s_nop 0
	v_cvt_pk_bf16_f32 v6, v194, v195
	v_lshlrev_b32_e32 v226, 16, v7
	v_and_b32_e32 v227, 0xffff0000, v7
	v_pk_add_f32 v[226:227], v[230:231], v[226:227]
	s_nop 0
	v_cvt_pk_bf16_f32 v7, v226, v227
	global_store_dwordx4 v[16:17], v[4:7], off offset:256
	v_lshlrev_b32_e32 v194, 16, v8
	v_and_b32_e32 v195, 0xffff0000, v8
	v_pk_add_f32 v[194:195], v[196:197], v[194:195]
	s_nop 0
	v_cvt_pk_bf16_f32 v8, v194, v195
	v_lshlrev_b32_e32 v226, 16, v9
	v_and_b32_e32 v227, 0xffff0000, v9
	v_pk_add_f32 v[226:227], v[198:199], v[226:227]
	s_nop 0
	v_cvt_pk_bf16_f32 v9, v226, v227
	v_lshlrev_b32_e32 v194, 16, v10
	v_and_b32_e32 v195, 0xffff0000, v10
	v_pk_add_f32 v[194:195], v[228:229], v[194:195]
	s_nop 0
	v_cvt_pk_bf16_f32 v10, v194, v195
	v_lshlrev_b32_e32 v226, 16, v11
	v_and_b32_e32 v227, 0xffff0000, v11
	v_pk_add_f32 v[226:227], v[230:231], v[226:227]
	s_nop 0
	v_cvt_pk_bf16_f32 v11, v226, v227
	global_store_dwordx4 v[16:17], v[8:11], off offset:512
	v_lshlrev_b32_e32 v194, 16, v12
	v_and_b32_e32 v195, 0xffff0000, v12
	v_pk_add_f32 v[194:195], v[196:197], v[194:195]
	s_nop 0
	v_cvt_pk_bf16_f32 v12, v194, v195
	v_lshlrev_b32_e32 v226, 16, v13
	v_and_b32_e32 v227, 0xffff0000, v13
	v_pk_add_f32 v[226:227], v[198:199], v[226:227]
	s_nop 0
	v_cvt_pk_bf16_f32 v13, v226, v227
	v_lshlrev_b32_e32 v194, 16, v14
	v_and_b32_e32 v195, 0xffff0000, v14
	v_pk_add_f32 v[194:195], v[228:229], v[194:195]
	s_nop 0
	v_cvt_pk_bf16_f32 v14, v194, v195
	v_lshlrev_b32_e32 v226, 16, v15
	v_and_b32_e32 v227, 0xffff0000, v15
	v_pk_add_f32 v[226:227], v[230:231], v[226:227]
	s_nop 0
	v_cvt_pk_bf16_f32 v15, v226, v227
	global_store_dwordx4 v[16:17], v[12:15], off offset:768
	v_lshlrev_b32_e32 v194, 16, v204
	v_and_b32_e32 v195, 0xffff0000, v204
	v_pk_add_f32 v[194:195], v[196:197], v[194:195]
	s_nop 0
	v_cvt_pk_bf16_f32 v204, v194, v195
	v_lshlrev_b32_e32 v226, 16, v205
	v_and_b32_e32 v227, 0xffff0000, v205
	v_pk_add_f32 v[226:227], v[198:199], v[226:227]
	s_nop 0
	v_cvt_pk_bf16_f32 v205, v226, v227
	v_lshlrev_b32_e32 v194, 16, v206
	v_and_b32_e32 v195, 0xffff0000, v206
	v_pk_add_f32 v[194:195], v[228:229], v[194:195]
	s_nop 0
	v_cvt_pk_bf16_f32 v206, v194, v195
	v_lshlrev_b32_e32 v226, 16, v207
	v_and_b32_e32 v227, 0xffff0000, v207
	v_pk_add_f32 v[226:227], v[230:231], v[226:227]
	s_nop 0
	v_cvt_pk_bf16_f32 v207, v226, v227
	global_store_dwordx4 v[202:203], v[204:207], off
	v_lshlrev_b32_e32 v194, 16, v208
	v_and_b32_e32 v195, 0xffff0000, v208
	v_pk_add_f32 v[194:195], v[196:197], v[194:195]
	s_nop 0
	v_cvt_pk_bf16_f32 v208, v194, v195
	v_lshlrev_b32_e32 v226, 16, v209
	v_and_b32_e32 v227, 0xffff0000, v209
	v_pk_add_f32 v[226:227], v[198:199], v[226:227]
	s_nop 0
	v_cvt_pk_bf16_f32 v209, v226, v227
	v_lshlrev_b32_e32 v194, 16, v210
	v_and_b32_e32 v195, 0xffff0000, v210
	v_pk_add_f32 v[194:195], v[228:229], v[194:195]
	s_nop 0
	v_cvt_pk_bf16_f32 v210, v194, v195
	v_lshlrev_b32_e32 v226, 16, v211
	v_and_b32_e32 v227, 0xffff0000, v211
	v_pk_add_f32 v[226:227], v[230:231], v[226:227]
	s_nop 0
	v_cvt_pk_bf16_f32 v211, v226, v227
	global_store_dwordx4 v[202:203], v[208:211], off offset:256
	v_lshlrev_b32_e32 v194, 16, v212
	v_and_b32_e32 v195, 0xffff0000, v212
	v_pk_add_f32 v[194:195], v[196:197], v[194:195]
	s_nop 0
	v_cvt_pk_bf16_f32 v212, v194, v195
	v_lshlrev_b32_e32 v226, 16, v213
	v_and_b32_e32 v227, 0xffff0000, v213
	v_pk_add_f32 v[226:227], v[198:199], v[226:227]
	s_nop 0
	v_cvt_pk_bf16_f32 v213, v226, v227
	v_lshlrev_b32_e32 v194, 16, v214
	v_and_b32_e32 v195, 0xffff0000, v214
	v_pk_add_f32 v[194:195], v[228:229], v[194:195]
	s_nop 0
	v_cvt_pk_bf16_f32 v214, v194, v195
	v_lshlrev_b32_e32 v226, 16, v215
	v_and_b32_e32 v227, 0xffff0000, v215
	v_pk_add_f32 v[226:227], v[230:231], v[226:227]
	s_nop 0
	v_cvt_pk_bf16_f32 v215, v226, v227
	global_store_dwordx4 v[202:203], v[212:215], off offset:512
	v_lshlrev_b32_e32 v194, 16, v216
	v_and_b32_e32 v195, 0xffff0000, v216
	v_pk_add_f32 v[194:195], v[196:197], v[194:195]
	s_nop 0
	v_cvt_pk_bf16_f32 v216, v194, v195
	v_lshlrev_b32_e32 v226, 16, v217
	v_and_b32_e32 v227, 0xffff0000, v217
	v_pk_add_f32 v[226:227], v[198:199], v[226:227]
	s_nop 0
	v_cvt_pk_bf16_f32 v217, v226, v227
	v_lshlrev_b32_e32 v194, 16, v218
	v_and_b32_e32 v195, 0xffff0000, v218
	v_pk_add_f32 v[194:195], v[228:229], v[194:195]
	s_nop 0
	v_cvt_pk_bf16_f32 v218, v194, v195
	v_lshlrev_b32_e32 v226, 16, v219
	v_and_b32_e32 v227, 0xffff0000, v219
	v_pk_add_f32 v[226:227], v[230:231], v[226:227]
	s_nop 0
	v_cvt_pk_bf16_f32 v219, v226, v227
	global_store_dwordx4 v[202:203], v[216:219], off offset:768
	s_mov_b64 vcc, 0x10000
	s_nop 1
	v_lshl_add_u64 v[16:17], v[16:17], 0, vcc
	s_add_i32 s16, s16, 1
	s_cmp_lg_u32 s16, 2
	s_cbranch_scc1 .Lab_loop
